# MLA attention role split: waves 4-7 one barrier behind waves 0-3, two barriers per tile, lead waves issue all LDS-DMA
# baseline (speedup 1.0000x reference)
; template <int TYPE>
; __device__ __forceinline__ void attn_item(const Params& p, int layer, int head, int qb, int mode, LAS unsigned char* lds) {
;     constexpr int DQK = TYPE == 0 ? 192 : 128, NQ = DQK / 16, SHM_K = 64 * DQK * 2;
;     constexpr int OFF_K = 2 * SHM_V, OFF_B = OFF_K + 2 * SHM_K;
;     const int tid = opaque_tid(), wid = __builtin_amdgcn_readfirstlane(tid >> 6), lane = tid & 63, r32 = lane & 31, hi = lane >> 5;
;     const int P0 = qb * 256, qrow = P0 + wid * 32 + r32;
;     const bf16_t* Qb; int ldq; const bf16_t* Kn; int ldk; const bf16_t* Vp; int ldv;
;     if (TYPE == 0) { Qb = (const bf16_t*)(p.ws + WS_QM) + head * 192; ldq = 1536; Kn = (const bf16_t*)(p.ws + WS_KV) + head * 256; ldk = 2048; Vp = Kn + 128; ldv = 2048; }
;     else { Qb = (const bf16_t*)(p.ws + WS_QF) + head * 128; ldq = 1024; Kn = (const bf16_t*)(p.ws + WS_KF) + head * 128; ldk = 1024; Vp = (const bf16_t*)(p.ws + WS_Z) + 3072 + head * 128; ldv = ZLD; }
;     const bf16_t* Krp = (const bf16_t*)(p.ws + WS_KR);
;     const float* bias = (const float*)(p.ws + WS_BK) + (size_t)head * MROWS;
;     ...
;     const int my_kmax = KMAX(qrow);
;     const int w_first = KMAX(P0 + wid * 32), w_last = KMAX(P0 + wid * 32 + 31);
;     int blk_kmax = KMAX(P0 + 255); if (blk_kmax > MROWS - 1) blk_kmax = MROWS - 1;
;     const int NT = blk_kmax / 64 + 1;
;     bf16x8 qr[NQ];
; #pragma unroll
;     for (int d0 = 0; d0 < NQ; ++d0) qr[d0] = *(const bf16x8*)(Qb + (size_t)qrow * ldq + d0 * 16 + hi * 8);
;     LAS unsigned char* V_lds = lds; LAS unsigned char* K_lds = lds + OFF_K; LAS float* B_lds = (LAS float*)(lds + OFF_B);
;     LAS float* wsl = (LAS float*)(lds + LDS_BYTES - 4096) + wid * 64;
;     const int vb0 = (int)(unsigned)(uintptr_t)V_lds + v_rd_base(lane);
;     unsigned offK[2], offV[2], offR;
; __device__ __forceinline__ void phase_attn(const Params& p, int layer, LAS unsigned char* lds) {
;     int* ctr = (int*)(p.ws + WS_CTR) + layer;
;     LAS int* sitem = (LAS int*)(lds + LDS_BYTES - 16);
;     for (;;) {
;         if (opaque_tid() == 0) *sitem = atomicAdd(ctr, 1);
;         __syncthreads();
;         const int it = *sitem;
;         __syncthreads();
;         if (it >= 464 + 264) break;
;         if (it < 264) attn_item<1>(p, layer, it & 7, 32 - (it >> 3), 0, lds);
;         else { const int e = MLA_ORDER[(it - 264) >> 3]; attn_item<0>(p, layer, it & 7, e & 63, e >> 6, lds); }
.LBB0_813:
	s_or_b64 exec, exec, s[0:1]
	v_readlane_b32 s0, v254, 10
	s_waitcnt vmcnt(0) lgkmcnt(0)
	s_barrier
	v_mov_b32_e32 v0, s0
	ds_read_b32 v0, v0
	s_movk_i32 s0, 0x2d7
	s_waitcnt lgkmcnt(0)
	s_barrier
	v_cmp_lt_i32_e32 vcc, s0, v0
	v_readfirstlane_b32 s42, v0
	s_mov_b64 s[0:1], -1
	s_cbranch_vccnz .LBB0_810
	s_cmpk_gt_i32 s42, 0x107
	s_cbranch_scc0 .LBB0_842
	s_add_i32 s0, s42, 0xfffffef8
	s_lshr_b32 s2, s0, 3
	s_getpc_b64 s[0:1]
	s_add_u32 s0, s0, MLA_ORDER@rel32@lo+4
	s_addc_u32 s1, s1, MLA_ORDER@rel32@hi+12
	v_mov_b32_e32 v0, s2
	global_load_sbyte v9, v0, s[0:1]
	v_mov_b32_e32 v2, v210
	s_and_b32 s5, s42, 7
	v_readfirstlane_b32 s6, v2
	s_ashr_i32 s13, s6, 6
	s_lshl_b32 s4, s13, 5
	s_mul_i32 s3, s5, 0x180
	v_and_b32_e32 v226, 31, v2
	v_and_b32_e32 v227, 63, v2
	v_lshlrev_b32_e32 v5, 3, v2
	v_bfe_u32 v225, v2, 5, 1
	v_bfe_u32 v223, v2, 4, 2
	v_and_b32_e32 v5, 24, v5
	s_movk_i32 s30, 0x60
	v_lshrrev_b32_e32 v6, 1, v2
	v_lshlrev_b32_e32 v0, 4, v225
	v_and_b32_e32 v224, 15, v2
	v_bfe_u32 v3, v2, 2, 2
	v_and_b32_e32 v4, 32, v2
	v_and_b32_e32 v6, 8, v6
	v_or_b32_e32 v13, v6, v3
	s_mov_b64 s[36:37], 0x100
	v_bfe_u32 v7, v2, 3, 3
	v_bitop3_b32 v8, v7, v2, 7 bitop3:0x78
	v_lshlrev_b32_e32 v7, 7, v7
	v_lshlrev_b32_e32 v8, 4, v8
	s_waitcnt vmcnt(0)
	v_readfirstlane_b32 s1, v9
	s_and_b32 s25, s1, 63
	s_lshl_b32 s2, s25, 8
	s_and_b32 s0, s1, 0xff
	s_bfe_u32 s24, s1, 0x20006
	s_add_i32 s2, s4, s2
	s_add_u32 s10, s21, s3
	v_readlane_b32 s3, v254, 60
	s_addc_u32 s11, s3, 0
	v_or_b32_e32 v9, s2, v226
	s_lshl_b32 s19, s5, 9
	v_readlane_b32 s3, v254, 61
	v_mov_b64_e32 v[10:11], s[10:11]
	s_movk_i32 s11, 0xc00
	s_add_u32 s7, s3, s19
	v_readlane_b32 s3, v254, 62
	v_mad_i64_i32 v[10:11], s[28:29], v9, s11, v[10:11]
	s_addc_u32 s10, s3, 0
	s_lshl_b32 s3, s25, 2
	s_and_b32 s28, s6, 0x3fffffc0
	s_lshl_b32 s14, s13, 1
	s_add_i32 s29, s13, 8
	s_lshl_b32 s12, s13, 2
	s_and_b32 s11, s6, 64
	s_add_i32 s6, s3, 4
	s_and_b32 s18, s14, 4
	s_lshl_b32 s3, s29, 2
	v_lshl_or_b32 v14, s29, 6, v227
	s_lshl_b32 s14, s29, 1
	s_lshl_b32 s28, s28, 2
	v_or_b32_e32 v12, s12, v223
	s_and_b32 s12, s12, 0xffff0
	v_or_b32_e32 v15, s3, v223
	v_and_or_b32 v14, v14, s30, v5
	s_and_b32 s30, s3, 0xffff0
	s_and_b32 s31, s14, 4
	s_add_i32 s3, s28, 0
	v_lshl_add_u64 v[10:11], v[10:11], 0, v[0:1]
	s_or_b32 s29, s12, s18
	s_or_b32 s14, s30, s31
	s_add_i32 s3, s3, 0x1f000
	v_or3_b32 v9, v4, s11, v5
	global_load_dwordx4 v[130:133], v[10:11], off
	global_load_dwordx4 v[134:137], v[10:11], off offset:32
	global_load_dwordx4 v[138:141], v[10:11], off offset:64
	global_load_dwordx4 v[142:145], v[10:11], off offset:96
	global_load_dwordx4 v[146:149], v[10:11], off offset:128
	global_load_dwordx4 v[150:153], v[10:11], off offset:160
	global_load_dwordx4 v[154:157], v[10:11], off offset:192
	global_load_dwordx4 v[158:161], v[10:11], off offset:224
	global_load_dwordx4 v[162:165], v[10:11], off offset:256
	global_load_dwordx4 v[166:169], v[10:11], off offset:288
	global_load_dwordx4 v[170:173], v[10:11], off offset:320
	global_load_dwordx4 v[174:177], v[10:11], off offset:352
	v_bitop3_b32 v10, v12, v224, 7 bitop3:0x6c
	s_cmp_lt_u32 s25, 33
	v_lshlrev_b32_e32 v11, 1, v9
	v_lshlrev_b32_e32 v9, 4, v10
	v_or_b32_e32 v10, s29, v13
	s_cselect_b32 s33, s6, 0x84
	v_lshl_or_b32 v17, v12, 12, v9
	v_lshl_or_b32 v12, v10, 12, v11
	v_or_b32_e32 v11, s14, v13
	s_add_i32 s14, s33, 4
	s_lshl_b32 s6, s13, 10
	s_lshr_b32 s14, s14, 1
	s_cmp_eq_u32 s24, 1
	s_sext_i32_i16 s1, s1
	s_cselect_b32 s40, s14, s33
	s_cmp_lt_i32 s1, 0
	s_cselect_b32 s14, s14, 3
	s_lshl_b64 s[38:39], s[14:15], 18
	s_add_u32 s28, s7, s38
	s_addc_u32 s29, s10, s39
	s_and_b32 s1, s14, 1
	s_mul_i32 s7, s1, 0x6000
	s_add_i32 s7, s7, 0
	s_lshl_b32 s1, s1, 13
	s_add_i32 s7, s7, s6
	v_mov_b32_e32 v13, v1
	v_bitop3_b32 v16, v15, v224, 7 bitop3:0x6c
	s_add_i32 m0, s7, 0x8000
	v_lshl_add_u64 v[12:13], s[28:29], 0, v[12:13]
	s_sub_i32 s1, s7, s1
	v_lshlrev_b32_e32 v10, 4, v16
	global_load_lds_dwordx4 v17, s[28:29]
	v_lshl_add_u64 v[12:13], v[12:13], 0, s[36:37]
	s_mov_b32 m0, s1
	v_lshlrev_b32_e32 v14, 1, v14
	v_lshl_or_b32 v15, v15, 12, v10
	global_load_lds_dwordx4 v[12:13], off
	s_add_i32 m0, s7, 0xa000
	v_lshl_or_b32 v14, v11, 12, v14
	global_load_lds_dwordx4 v15, s[28:29]
	v_mov_b32_e32 v15, v1
	s_add_i32 m0, s1, 0x2000
	v_lshl_add_u64 v[12:13], s[28:29], 0, v[14:15]
	s_cmp_gt_u32 s0, 63
	v_lshl_add_u64 v[12:13], v[12:13], 0, s[36:37]
	s_cselect_b64 s[36:37], -1, 0
	s_cmp_lt_u32 s0, 64
	s_cselect_b32 s7, s33, s40
	s_lshl_b64 s[40:41], s[14:15], 13
	v_readlane_b32 s0, v254, 63
	s_add_u32 s0, s0, s40
	v_readlane_b32 s1, v255, 0
	s_addc_u32 s1, s1, s41
	s_bitcmp1_b32 s14, 0
	s_cselect_b32 s10, 0x6000, 0
	s_add_i32 s10, s10, 0
	s_add_i32 s10, s10, s6
	v_or3_b32 v11, v8, v7, s6
	global_load_lds_dwordx4 v[12:13], off
	s_add_i32 m0, s10, 0xc000
	s_sub_i32 s7, s7, s14
	global_load_lds_dwordx4 v11, s[0:1]
	s_waitcnt vmcnt(0)
	s_cmp_lt_i32 s7, 1
	v_cmp_gt_u32_e64 s[0:1], 32, v227
	s_waitcnt vmcnt(0) lgkmcnt(0)
	s_barrier
; template <int TYPE>
; __device__ __forceinline__ void attn_item(const Params& p, int layer, int head, int qb, int mode, LAS unsigned char* lds) {
;     ...
;     for (int it2 = 0; it2 < ntiles; ++it2) {
;         const int t = TYPE == 1 ? tfirst - it2 : tfirst + it2, tn = TYPE == 1 ? t - 1 : t + 1;
;         const int bf = t & 1, kbase = t * 64;
;         if (it2 + 1 < ntiles) { ADMA(tn, bf ^ 1); }
;         if (kbase <= w_last) {
;     ...
;         asm volatile("s_waitcnt vmcnt(0)" ::: "memory");
;         __syncthreads();
	s_cbranch_scc1 .LBB0_830
	v_lshlrev_b32_e32 v13, 4, v227
	v_lshlrev_b32_e32 v12, 3, v227
	v_and_b32_e32 v13, 0xc0, v13
	v_lshlrev_b32_e32 v14, 1, v227
	v_and_b32_e32 v11, 7, v2
	v_and_or_b32 v13, v12, 24, v13
	v_and_b32_e32 v14, 32, v14
	v_and_b32_e32 v12, 0x100, v12
	v_or3_b32 v12, v13, v14, v12
	v_xor_b32_e32 v13, v225, v11
	s_or_b32 s10, s2, 63
	v_lshlrev_b32_e32 v230, 4, v13
	v_bitop3_b32 v13, v225, v11, 2 bitop3:0x36
	v_lshlrev_b32_e32 v231, 4, v13
	v_bitop3_b32 v13, v225, v11, 4 bitop3:0x36
	s_add_u32 s28, s40, 0x27d62000
	v_lshlrev_b32_e32 v232, 4, v13
	v_add_u32_e32 v234, 0, v12
	s_addc_u32 s29, s41, 0
	v_add3_u32 v12, s6, v7, v8
	v_mov_b32_e32 v13, v1
	s_or_b32 s19, s38, s19
	v_lshl_add_u64 v[200:201], s[28:29], 0, v[12:13]
	s_add_u32 s28, s19, 0x25ca0100
	s_addc_u32 s29, s39, 0
	s_add_i32 s31, s31, s30
	s_lshl_b32 s30, s13, 6
	s_addk_i32 s30, 0x200
	v_or_b32_e32 v8, s30, v227
	v_add_u32_e32 v7, s31, v6
	v_lshlrev_b32_e32 v8, 1, v8
	v_and_b32_e32 v2, 3, v2
	v_add_lshl_u32 v7, v7, v3, 12
	v_and_b32_e32 v8, 0xc0, v8
	v_lshlrev_b32_e32 v2, 4, v2
	s_add_i32 s18, s18, s12
	v_or3_b32 v12, v7, v8, v2
	v_add3_u32 v2, s18, v6, v3
	v_add_u32_e32 v3, s11, v4
	s_add_u32 s18, s19, 0x25ca0000
	v_add_lshl_u32 v3, v3, v5, 1
	s_addc_u32 s19, s39, 0
	s_lshl_b32 s11, s13, 14
	v_lshl_or_b32 v2, v2, 12, v3
	v_mov_b32_e32 v3, v1
	s_add_i32 s12, s11, 0x20000
	v_lshlrev_b32_e32 v4, 12, v223
	v_lshl_add_u64 v[204:205], s[28:29], 0, v[2:3]
	v_or3_b32 v2, s12, v4, v10
	v_bitop3_b32 v11, v225, v11, 6 bitop3:0x36
	v_lshl_add_u64 v[206:207], s[18:19], 0, v[2:3]
	v_or3_b32 v2, s11, v4, v9
	v_mov_b32_e32 v16, v1
	v_mov_b32_e32 v17, v1
	v_lshlrev_b32_e32 v233, 4, v11
	v_lshl_add_u64 v[202:203], s[28:29], 0, v[12:13]
	v_lshl_add_u64 v[208:209], s[18:19], 0, v[2:3]
	v_mov_b32_e32 v2, v1
	v_mov_b32_e32 v4, v1
	v_mov_b32_e32 v5, v1
	v_mov_b32_e32 v6, v1
	v_mov_b32_e32 v7, v1
	v_mov_b32_e32 v8, v1
	v_mov_b32_e32 v9, v1
	v_mov_b32_e32 v10, v1
	v_mov_b32_e32 v11, v1
	v_mov_b32_e32 v12, v1
	v_mov_b32_e32 v14, v1
	v_mov_b32_e32 v15, v1
	v_mov_b64_e32 v[64:65], v[16:17]
	v_mov_b64_e32 v[48:49], v[16:17]
	v_mov_b64_e32 v[32:33], v[16:17]
	v_lshlrev_b32_e32 v228, 8, v226
	v_lshlrev_b32_e32 v229, 7, v226
	v_lshl_add_u32 v235, v226, 2, s3
	s_lshl_b32 s11, s14, 6
	s_mov_b32 s12, 0
	v_mov_b32_e32 v199, 0
	v_mov_b32_e32 v198, 0xf149f2ca
	v_add_u32_e32 v0, s3, v0
	v_mov_b64_e32 v[62:63], v[14:15]
	v_mov_b64_e32 v[60:61], v[12:13]
	v_mov_b64_e32 v[58:59], v[10:11]
	v_mov_b64_e32 v[56:57], v[8:9]
	v_mov_b64_e32 v[54:55], v[6:7]
	v_mov_b64_e32 v[52:53], v[4:5]
	v_mov_b64_e32 v[50:51], v[2:3]
	v_mov_b64_e32 v[46:47], v[14:15]
	v_mov_b64_e32 v[44:45], v[12:13]
	v_mov_b64_e32 v[42:43], v[10:11]
	v_mov_b64_e32 v[40:41], v[8:9]
	v_mov_b64_e32 v[38:39], v[6:7]
	v_mov_b64_e32 v[36:37], v[4:5]
	v_mov_b64_e32 v[34:35], v[2:3]
	v_mov_b64_e32 v[30:31], v[14:15]
	v_mov_b64_e32 v[28:29], v[12:13]
	v_mov_b64_e32 v[26:27], v[10:11]
	v_mov_b64_e32 v[24:25], v[8:9]
	v_mov_b64_e32 v[22:23], v[6:7]
	v_mov_b64_e32 v[20:21], v[4:5]
	v_mov_b64_e32 v[18:19], v[2:3]
	v_readlane_b32 s31, v254, 57
	v_readlane_b32 s30, v254, 23
	v_readfirstlane_b32 s100, v210
	s_mov_b32 s101, 1
	s_bitcmp1_b32 s100, 8
	s_cbranch_scc0 .Lrs_enter
	s_mov_b32 s101, 0
	s_barrier
.Lrs_enter:
	s_branch .LBB0_819
.LBB0_817:
	v_add_f32_e32 v66, v237, v238
	v_fmac_f32_e32 v66, v199, v236
	v_mov_b32_e32 v199, v66
.LBB0_818:
	s_mov_b64 s[18:19], 0x2000
	v_lshl_add_u64 v[200:201], v[200:201], 0, s[18:19]
	v_lshl_add_u64 v[202:203], v[202:203], 0, s[82:83]
	v_lshl_add_u64 v[204:205], v[204:205], 0, s[82:83]
	v_lshl_add_u64 v[206:207], v[206:207], 0, s[82:83]
	v_lshl_add_u64 v[208:209], v[208:209], 0, s[82:83]
	s_add_i32 s11, s11, 64
	s_and_b64 vcc, exec, s[38:39]
	s_cbranch_vccnz .Lrs_b2_last
	s_waitcnt vmcnt(4) lgkmcnt(0)
	s_barrier
	s_branch .LBB0_819
.Lrs_b2_last:
	s_waitcnt vmcnt(0) lgkmcnt(0)
	s_barrier
	s_cmp_eq_u32 s101, 0
	s_cbranch_scc1 .Lrs_exit
	s_barrier

; template <int TYPE>
; __device__ __forceinline__ void attn_item(const Params& p, int layer, int head, int qb, int mode, LAS unsigned char* lds) {
;     ...
;         if (it2 + 1 < ntiles) { ADMA(tn, bf ^ 1); }
.LBB0_819:
	s_add_i32 s18, s14, s12
	s_and_b32 s28, s18, 1
	s_add_i32 s12, s12, 1
	s_cmp_ge_i32 s12, s7
	s_cselect_b64 s[38:39], -1, 0
	s_and_b64 vcc, exec, s[38:39]
	s_cbranch_vccnz .LBB0_821
	s_cmp_eq_u32 s101, 0
	s_cbranch_scc1 .LBB0_821
	s_xor_b32 s19, s28, 1
	s_mul_i32 s29, s19, 0x6000
	s_add_i32 s29, s29, s6
	v_lshl_add_u64 v[194:195], s[34:35], 0, v[208:209]
	s_add_i32 m0, s29, 0x8000
	s_nop 0
	global_load_lds_dwordx4 v[194:195], off
	v_add_co_u32_e32 v196, vcc, 0x10000, v194
	s_add_i32 m0, s29, 0x9000
	s_nop 0
	v_addc_co_u32_e32 v197, vcc, 0, v195, vcc
	global_load_lds_dwordx4 v[196:197], off
	v_lshl_add_u64 v[194:195], s[34:35], 0, v[206:207]
	s_add_i32 m0, s29, 0xa000
	s_nop 0
	global_load_lds_dwordx4 v[194:195], off
	v_add_co_u32_e32 v196, vcc, 0x10000, v194
	s_add_i32 m0, s29, 0xb000
	s_nop 0
	v_addc_co_u32_e32 v197, vcc, 0, v195, vcc
	global_load_lds_dwordx4 v[196:197], off
	v_lshl_add_u64 v[194:195], s[34:35], 0, v[200:201]
	s_add_i32 m0, s29, 0xc000
	s_nop 0
	global_load_lds_dwordx4 v[194:195], off
	v_add_co_u32_e32 v196, vcc, 0x1000, v194
	s_add_i32 m0, s29, 0xd000
	s_nop 0
	v_addc_co_u32_e32 v197, vcc, 0, v195, vcc
	global_load_lds_dwordx4 v[196:197], off

; template <int TYPE>
; __device__ __forceinline__ void attn_item(const Params& p, int layer, int head, int qb, int mode, LAS unsigned char* lds) {
;     ...
;             if (t == T0) {
;                 const int lo = (PADR & 63) - 4 * hi; const float NEGI = -__builtin_inff();
; #pragma unroll
;                 for (int r = 0; r < 16; ++r) { const int c = (r & 3) + 8 * (r >> 2); if (c < lo) p0[r] = NEGI; if (c + 32 < lo) p1[r] = NEGI; }
;             }
;             float pmax = p0[0];
; #pragma unroll
;             for (int r = 1; r < 16; ++r) pmax = fmaxf(pmax, p0[r]);
; #pragma unroll
;             for (int r = 0; r < 16; ++r) pmax = fmaxf(pmax, p1[r]);
;             { auto rr = __builtin_amdgcn_permlane32_swap(__float_as_uint(pmax), __float_as_uint(pmax), false, false);
;               pmax = fmaxf(__uint_as_float(rr[0]), __uint_as_float(rr[1])); }
;             float mn, alpha;
;             if (__all((pmax - m_reg) <= (TYPE == 1 ? 2.0f : 11.5f))) { mn = m_reg; alpha = 1.f; }
;             else { mn = fmaxf(m_reg, pmax); alpha = __builtin_amdgcn_exp2f(m_reg - mn); m_reg = mn; }
;             float ps = 0.f;
; #pragma unroll
;             for (int r = 0; r < 16; ++r) { p0[r] = __builtin_amdgcn_exp2f(p0[r] - mn); p1[r] = __builtin_amdgcn_exp2f(p1[r] - mn); ps += p0[r] + p1[r]; }
;             { auto rr = __builtin_amdgcn_permlane32_swap(__float_as_uint(ps), __float_as_uint(ps), false, false);
;               ps = __uint_as_float(rr[0]) + __uint_as_float(rr[1]); }
;             l_reg = l_reg * alpha + ps;
;             bf16x8 pa0, pa1, pa2, pa3;
;     ...
;             PK4(p0, 0, pa0); PK4(p0, 8, pa1); PK4(p1, 0, pa2); PK4(p1, 8, pa3);
.Lrs_bar1:
	s_and_b64 vcc, exec, s[38:39]
	s_cbranch_vccnz .Lrs_b1_last
	s_waitcnt vmcnt(6) lgkmcnt(0)
	s_barrier
	s_cmp_eq_u32 s101, 0
	s_cbranch_scc1 .Lrs_b1_done
	s_xor_b32 s19, s28, 1
	s_lshl_b32 s19, s19, 14
	s_add_i32 s19, s19, s6
	v_lshl_add_u64 v[194:195], s[34:35], 0, v[204:205]
	s_mov_b32 m0, s19
	s_nop 0
	global_load_lds_dwordx4 v[194:195], off
	v_add_co_u32_e32 v196, vcc, 0x10000, v194
	s_add_i32 m0, s19, 0x1000
	s_nop 0
	v_addc_co_u32_e32 v197, vcc, 0, v195, vcc
	global_load_lds_dwordx4 v[196:197], off
	v_lshl_add_u64 v[194:195], s[34:35], 0, v[202:203]
	s_add_i32 m0, s19, 0x2000
	s_nop 0
	global_load_lds_dwordx4 v[194:195], off
	v_add_co_u32_e32 v196, vcc, 0x10000, v194
	s_add_i32 m0, s19, 0x3000
	s_nop 0
	v_addc_co_u32_e32 v197, vcc, 0, v195, vcc
	global_load_lds_dwordx4 v[196:197], off
	s_branch .Lrs_b1_done
.Lrs_b1_last:
	s_waitcnt vmcnt(0) lgkmcnt(0)
	s_barrier
.Lrs_b1_done:
	s_cmp_gt_i32 s11, s10
	s_cbranch_scc1 .LBB0_818
	s_cmp_eq_u32 s18, 3
	s_cselect_b64 vcc, -1, 0
	s_nop 7
	v_cndmask_b32_e32 v82, v82, v219, vcc
	v_cndmask_b32_e32 v83, v83, v219, vcc
	v_max_f32_e32 v98, v83, v83
	v_max_f32_e32 v99, v82, v82
	v_cndmask_b32_e32 v85, v85, v219, vcc
	v_cndmask_b32_e32 v84, v84, v219, vcc
	v_max_f32_e32 v98, v99, v98
	v_cndmask_b32_e32 v87, v87, v219, vcc
	v_cndmask_b32_e32 v86, v86, v219, vcc
	v_max3_f32 v98, v98, v84, v85
	v_cndmask_b32_e32 v89, v89, v219, vcc
	v_cndmask_b32_e32 v88, v88, v219, vcc
	v_max3_f32 v98, v98, v86, v87
	v_cndmask_b32_e32 v91, v91, v219, vcc
	v_cndmask_b32_e32 v90, v90, v219, vcc
	v_max3_f32 v98, v98, v88, v89
	v_cndmask_b32_e32 v93, v93, v219, vcc
	v_cndmask_b32_e32 v92, v92, v219, vcc
	v_max3_f32 v98, v98, v90, v91
	v_cndmask_b32_e32 v95, v95, v219, vcc
	v_cndmask_b32_e32 v94, v94, v219, vcc
	v_max3_f32 v98, v98, v92, v93
	v_cndmask_b32_e32 v97, v97, v219, vcc
	v_cndmask_b32_e32 v96, v96, v219, vcc
	v_max3_f32 v98, v98, v94, v95
	v_cndmask_b32_e32 v67, v67, v219, vcc
	v_cndmask_b32_e32 v66, v66, v219, vcc
	v_max3_f32 v98, v98, v96, v97
	v_cndmask_b32_e32 v69, v69, v219, vcc
	v_cndmask_b32_e32 v68, v68, v219, vcc
	v_max3_f32 v98, v98, v66, v67
	v_cndmask_b32_e32 v71, v71, v219, vcc
	v_cndmask_b32_e32 v70, v70, v219, vcc
	v_max3_f32 v98, v98, v68, v69
	v_cndmask_b32_e32 v73, v73, v219, vcc
	v_cndmask_b32_e32 v72, v72, v219, vcc
	v_max3_f32 v98, v98, v70, v71
	v_max3_f32 v98, v98, v72, v73
	v_max3_f32 v98, v98, v74, v75
	v_max3_f32 v98, v98, v76, v77
	v_max3_f32 v98, v98, v78, v79
	v_max3_f32 v98, v98, v80, v81
	v_mov_b32_e32 v99, v98
	s_nop 1
	v_permlane32_swap_b32_e32 v98, v99
	v_max_f32_e32 v99, v99, v99
	v_max_f32_e32 v98, v98, v98
	v_max_f32_e32 v98, v98, v99
	v_sub_f32_e32 v99, v98, v198
	s_mov_b32 s18, 0x41380000
	v_cmp_ge_f32_e32 vcc, s18, v99
	s_cmp_eq_u64 vcc, exec
	v_max_f32_e32 v99, v198, v198
	v_max_f32_e32 v98, v99, v98
	s_cselect_b64 vcc, -1, 0
	v_sub_f32_e32 v99, v198, v98
	v_cndmask_b32_e32 v198, v98, v198, vcc
	v_sub_f32_e32 v82, v82, v198
	v_sub_f32_e32 v66, v66, v198
	v_exp_f32_e32 v82, v82
	v_exp_f32_e32 v66, v66
	v_sub_f32_e32 v83, v83, v198
	v_sub_f32_e32 v67, v67, v198
	v_exp_f32_e32 v83, v83
	v_exp_f32_e32 v67, v67
	v_sub_f32_e32 v84, v84, v198
	v_sub_f32_e32 v68, v68, v198
	v_exp_f32_e32 v84, v84
	v_exp_f32_e32 v68, v68
	v_sub_f32_e32 v85, v85, v198
	v_sub_f32_e32 v69, v69, v198
	v_exp_f32_e32 v85, v85
	v_exp_f32_e32 v69, v69
	v_sub_f32_e32 v86, v86, v198
	v_sub_f32_e32 v70, v70, v198
	v_exp_f32_e32 v98, v99
	v_add_f32_e32 v99, v66, v82
	v_exp_f32_e32 v86, v86
	v_exp_f32_e32 v70, v70
	v_sub_f32_e32 v87, v87, v198
	v_sub_f32_e32 v71, v71, v198
	v_add_f32_e32 v99, 0, v99
	v_add_f32_e32 v100, v67, v83
	v_exp_f32_e32 v87, v87
	v_exp_f32_e32 v71, v71
	v_sub_f32_e32 v88, v88, v198
	v_sub_f32_e32 v72, v72, v198
	v_add_f32_e32 v99, v100, v99
	v_add_f32_e32 v100, v68, v84
	v_exp_f32_e32 v88, v88
	v_exp_f32_e32 v72, v72
	v_sub_f32_e32 v89, v89, v198
	v_sub_f32_e32 v73, v73, v198
	v_add_f32_e32 v99, v100, v99
	v_add_f32_e32 v100, v69, v85
	v_exp_f32_e32 v89, v89
	v_exp_f32_e32 v73, v73
	v_sub_f32_e32 v90, v90, v198
	v_sub_f32_e32 v74, v74, v198
	v_add_f32_e32 v99, v100, v99
	v_add_f32_e32 v100, v70, v86
	v_exp_f32_e32 v90, v90
	v_exp_f32_e32 v74, v74
	v_sub_f32_e32 v91, v91, v198
	v_sub_f32_e32 v75, v75, v198
	v_add_f32_e32 v99, v100, v99
	v_add_f32_e32 v100, v71, v87
	v_exp_f32_e32 v91, v91
	v_exp_f32_e32 v75, v75
	v_sub_f32_e32 v92, v92, v198
	v_sub_f32_e32 v76, v76, v198
	v_add_f32_e32 v99, v100, v99
	v_add_f32_e32 v100, v72, v88
	v_exp_f32_e32 v92, v92
	v_exp_f32_e32 v76, v76
	v_sub_f32_e32 v93, v93, v198
	v_sub_f32_e32 v77, v77, v198
	v_add_f32_e32 v99, v100, v99
	v_add_f32_e32 v100, v73, v89
	v_exp_f32_e32 v93, v93
	v_exp_f32_e32 v77, v77
	v_sub_f32_e32 v94, v94, v198
	v_sub_f32_e32 v78, v78, v198
	v_add_f32_e32 v99, v100, v99
	v_add_f32_e32 v100, v74, v90
	v_exp_f32_e32 v94, v94
	v_exp_f32_e32 v78, v78
	v_sub_f32_e32 v95, v95, v198
	v_sub_f32_e32 v79, v79, v198
	v_add_f32_e32 v99, v100, v99
	v_add_f32_e32 v100, v75, v91
	v_exp_f32_e32 v95, v95
	v_exp_f32_e32 v79, v79
	v_sub_f32_e32 v96, v96, v198
	v_sub_f32_e32 v80, v80, v198
	v_add_f32_e32 v99, v100, v99
	v_add_f32_e32 v100, v76, v92
	v_exp_f32_e32 v96, v96
	v_exp_f32_e32 v80, v80
	v_sub_f32_e32 v97, v97, v198
	v_sub_f32_e32 v81, v81, v198
	v_add_f32_e32 v99, v100, v99
	v_add_f32_e32 v100, v77, v93
	v_exp_f32_e32 v97, v97
	v_exp_f32_e32 v81, v81
	v_add_f32_e32 v99, v100, v99
	v_add_f32_e32 v100, v78, v94
	v_add_f32_e32 v99, v100, v99
	v_add_f32_e32 v100, v79, v95
	v_add_f32_e32 v99, v100, v99
	v_add_f32_e32 v100, v80, v96
	v_add_f32_e32 v99, v100, v99
	v_add_f32_e32 v100, v81, v97
	v_add_f32_e32 v237, v100, v99
	v_cndmask_b32_e64 v236, v98, 1.0, vcc
	v_mov_b32_e32 v238, v237
	v_cvt_pk_bf16_f32 v178, v82, v83
	v_cvt_pk_bf16_f32 v179, v84, v85
	v_cvt_pk_bf16_f32 v180, v86, v87
	v_cvt_pk_bf16_f32 v181, v88, v89
	v_cvt_pk_bf16_f32 v182, v90, v91
	v_cvt_pk_bf16_f32 v183, v92, v93
	v_cvt_pk_bf16_f32 v184, v94, v95
	v_cvt_pk_bf16_f32 v185, v96, v97
	v_cvt_pk_bf16_f32 v186, v66, v67
	v_cvt_pk_bf16_f32 v187, v68, v69
	v_cvt_pk_bf16_f32 v188, v70, v71
	v_cvt_pk_bf16_f32 v189, v72, v73
	v_cvt_pk_bf16_f32 v190, v74, v75
	v_cvt_pk_bf16_f32 v191, v76, v77
	v_cvt_pk_bf16_f32 v192, v78, v79
	v_cvt_pk_bf16_f32 v193, v80, v81
	s_nop 1
	v_permlane32_swap_b32_e32 v237, v238
	v_permlane32_swap_b32_e32 v178, v180
	v_permlane32_swap_b32_e32 v179, v181
	v_permlane32_swap_b32_e32 v182, v184
	v_permlane32_swap_b32_e32 v183, v185
	v_permlane32_swap_b32_e32 v186, v188
	v_permlane32_swap_b32_e32 v187, v189
	v_permlane32_swap_b32_e32 v190, v192
	v_permlane32_swap_b32_e32 v191, v193
	v_cmp_gt_f32_e32 vcc, 1.0, v236
	s_cbranch_vccz .LBB0_826
; __device__ __forceinline__ int crow(int r, int hi) { return (r & 3) + 8 * (r >> 2) + 4 * hi; }
; template <int TYPE>
; __device__ __forceinline__ void attn_item(const Params& p, int layer, int head, int qb, int mode, LAS unsigned char* lds) {
;     ...
;             if (__any(alpha < 1.f)) {
;                 if (hi == 0) wsl[r32] = alpha;
;                 asm volatile("s_waitcnt lgkmcnt(0)" ::: "memory");
; #pragma unroll
;                 for (int r = 0; r < 16; ++r) { const float al = wsl[crow(r, hi)];
; #pragma unroll
;                     for (int d = 0; d < 4; ++d) o[d][r] *= al; }
;             }
	s_and_saveexec_b64 s[40:41], s[0:1]
	ds_write_b32 v235, v236
	s_or_b64 exec, exec, s[40:41]
	s_waitcnt lgkmcnt(0)
	ds_read_b128 v[66:69], v0 offset:96
	ds_read_b128 v[70:73], v0 offset:64
	ds_read_b128 v[74:77], v0 offset:32
	ds_read_b128 v[78:81], v0
	s_waitcnt lgkmcnt(0)
	v_pk_mul_f32 v[14:15], v[14:15], v[66:67]
	v_pk_mul_f32 v[10:11], v[10:11], v[70:71]
	v_pk_mul_f32 v[6:7], v[6:7], v[74:75]
	v_pk_mul_f32 v[16:17], v[16:17], v[68:69]
	v_pk_mul_f32 v[12:13], v[12:13], v[72:73]
	v_pk_mul_f32 v[8:9], v[8:9], v[76:77]
	v_pk_mul_f32 v[4:5], v[4:5], v[80:81]
	v_pk_mul_f32 v[2:3], v[2:3], v[78:79]
	v_pk_mul_f32 v[62:63], v[62:63], v[66:67]
	v_pk_mul_f32 v[58:59], v[58:59], v[70:71]
	v_pk_mul_f32 v[54:55], v[54:55], v[74:75]
	v_pk_mul_f32 v[64:65], v[64:65], v[68:69]
	v_pk_mul_f32 v[60:61], v[60:61], v[72:73]
	v_pk_mul_f32 v[56:57], v[56:57], v[76:77]
	v_pk_mul_f32 v[52:53], v[52:53], v[80:81]
	v_pk_mul_f32 v[50:51], v[50:51], v[78:79]
	v_pk_mul_f32 v[46:47], v[46:47], v[66:67]
	v_pk_mul_f32 v[42:43], v[42:43], v[70:71]
	v_pk_mul_f32 v[38:39], v[38:39], v[74:75]
	v_pk_mul_f32 v[48:49], v[48:49], v[68:69]
	v_pk_mul_f32 v[44:45], v[44:45], v[72:73]
	v_pk_mul_f32 v[40:41], v[40:41], v[76:77]
	v_pk_mul_f32 v[36:37], v[36:37], v[80:81]
	v_pk_mul_f32 v[34:35], v[34:35], v[78:79]
	v_pk_mul_f32 v[30:31], v[30:31], v[66:67]
	v_pk_mul_f32 v[26:27], v[26:27], v[70:71]
	v_pk_mul_f32 v[22:23], v[22:23], v[74:75]
	v_pk_mul_f32 v[32:33], v[32:33], v[68:69]
	v_pk_mul_f32 v[28:29], v[28:29], v[72:73]
	v_pk_mul_f32 v[24:25], v[24:25], v[76:77]
	v_pk_mul_f32 v[20:21], v[20:21], v[80:81]
	v_pk_mul_f32 v[18:19], v[18:19], v[78:79]
